# v44 + gMLP block LayerNorm: the second batch of eight 16-byte row loads issued together with the first (one memory round trip per 256x256 block instead of two)
# baseline (speedup 1.0000x reference)
; __device__ __forceinline__ void gm_ln_block(bf16_t* Vt, const float* S1, const float* S2, const float* lng, const float* lnb, int c0, int t0, int tid) {
;     const int tt = t0 + (tid & 31) * 8, r0 = tid >> 5;
;     float mu[8], rs[8];
;     { const f32x4 a0 = *(const f32x4*)(S1 + tt), a1 = *(const f32x4*)(S1 + tt + 4), b0 = *(const f32x4*)(S2 + tt), b1 = *(const f32x4*)(S2 + tt + 4);
; #pragma unroll
;       for (int e = 0; e < 8; ++e) { const float s1 = e < 4 ? a0[e & 3] : a1[e & 3], s2 = e < 4 ? b0[e & 3] : b1[e & 3]; mu[e] = s1 * (1.f / GMH); rs[e] = 1.0f / sqrtf(fmaxf(s2 * (1.f / GMH) - mu[e] * mu[e], 0.f) + EPS); } }
.LBB0_423:
	v_mov_b64_e32 v[0:1], s[68:69]
	v_cmp_lt_i64_e32 vcc, s[20:21], v[0:1]
	s_mov_b64 s[6:7], -1
	s_cbranch_vccz .LBB0_420
	v_lshl_or_b32 v16, s55, 8, v68
	v_ashrrev_i32_e32 v17, 31, v16
	v_lshlrev_b64 v[4:5], 2, v[16:17]
	v_lshl_add_u64 v[0:1], s[8:9], 0, v[4:5]
	v_lshl_add_u64 v[4:5], s[16:17], 0, v[4:5]
	s_load_dwordx4 s[24:27], s[4:5], 0x90
	global_load_dwordx4 v[8:11], v[0:1], off
	s_nop 0
	global_load_dwordx4 v[0:3], v[0:1], off offset:16
	s_nop 0
	global_load_dwordx4 v[12:15], v[4:5], off
	s_nop 0
	global_load_dwordx4 v[4:7], v[4:5], off offset:16
	v_lshl_add_u32 v52, s54, 8, v69
	v_lshl_add_u64 v[48:49], v[16:17], 1, s[14:15]
	s_waitcnt lgkmcnt(0)
	s_add_u32 s22, s24, s18
	s_addc_u32 s23, s25, s19
	s_add_u32 s24, s26, s18
	s_mov_b32 s26, 0x3a000000
	v_ashrrev_i32_e32 v53, 31, v52
	s_addc_u32 s25, s27, s19
	s_add_u32 s20, s20, s1
	s_addc_u32 s21, s21, s56
	s_waitcnt vmcnt(0)
	v_mov_b32_e32 v19, v2
	s_waitcnt vmcnt(0)
	v_mov_b32_e32 v18, v6
	v_pk_mul_f32 v[28:29], v[18:19], s[26:27] op_sel_hi:[1,0]
	s_nop 0
	v_fma_f32 v2, -v29, v29, v28
	v_max_f32_e32 v2, 0, v2
	v_add_f32_e32 v2, 0x358637bd, v2
	v_cmp_gt_f32_e32 vcc, s91, v2
	v_mul_f32_e32 v6, 0x4f800000, v2
	s_nop 0
	v_cndmask_b32_e32 v2, v2, v6, vcc
	v_sqrt_f32_e32 v6, v2
	s_nop 0
	v_add_u32_e32 v18, -1, v6
	v_fma_f32 v19, -v18, v6, v2
	v_cmp_ge_f32_e64 s[6:7], 0, v19
	v_add_u32_e32 v19, 1, v6
	s_nop 0
	v_cndmask_b32_e64 v18, v6, v18, s[6:7]
	v_fma_f32 v6, -v19, v6, v2
	v_cmp_lt_f32_e64 s[6:7], 0, v6
	s_nop 1
	v_cndmask_b32_e64 v6, v18, v19, s[6:7]
	v_mul_f32_e32 v18, 0x37800000, v6
	v_cndmask_b32_e32 v6, v6, v18, vcc
	v_cmp_class_f32_e32 vcc, v2, v254
	s_nop 1
	v_cndmask_b32_e32 v2, v6, v2, vcc
	v_div_scale_f32 v6, s[2:3], v2, v2, 1.0
	v_rcp_f32_e32 v18, v6
	s_nop 0
	v_fma_f32 v19, -v6, v18, 1.0
	v_fmac_f32_e32 v18, v19, v18
	v_div_scale_f32 v19, vcc, 1.0, v2, 1.0
	v_mul_f32_e32 v20, v19, v18
	v_fma_f32 v21, -v6, v20, v19
	v_fmac_f32_e32 v20, v21, v18
	v_fma_f32 v6, -v6, v20, v19
	v_div_fmas_f32 v6, v6, v18, v20
	v_mov_b32_e32 v18, v5
	v_mov_b32_e32 v19, v1
	v_pk_mul_f32 v[30:31], v[18:19], s[26:27] op_sel_hi:[1,0]
	v_div_fixup_f32 v28, v6, v2, 1.0
	v_fma_f32 v1, -v31, v31, v30
	v_max_f32_e32 v1, 0, v1
	v_add_f32_e32 v1, 0x358637bd, v1
	v_cmp_gt_f32_e32 vcc, s91, v1
	v_mul_f32_e32 v2, 0x4f800000, v1
	s_nop 0
	v_cndmask_b32_e32 v1, v1, v2, vcc
	v_sqrt_f32_e32 v2, v1
	s_nop 0
	v_add_u32_e32 v5, -1, v2
	v_fma_f32 v6, -v5, v2, v1
	v_cmp_ge_f32_e64 s[6:7], 0, v6
	v_add_u32_e32 v6, 1, v2
	s_nop 0
	v_cndmask_b32_e64 v5, v2, v5, s[6:7]
	v_fma_f32 v2, -v6, v2, v1
	v_cmp_lt_f32_e64 s[6:7], 0, v2
	s_nop 1
	v_cndmask_b32_e64 v2, v5, v6, s[6:7]
	v_mul_f32_e32 v5, 0x37800000, v2
	v_cndmask_b32_e32 v2, v2, v5, vcc
	v_cmp_class_f32_e32 vcc, v1, v254
	s_nop 1
	v_cndmask_b32_e32 v1, v2, v1, vcc
	v_div_scale_f32 v2, s[2:3], v1, v1, 1.0
	v_rcp_f32_e32 v5, v2
	s_nop 0
	v_fma_f32 v6, -v2, v5, 1.0
	v_fmac_f32_e32 v5, v6, v5
	v_div_scale_f32 v6, vcc, 1.0, v1, 1.0
	v_mul_f32_e32 v18, v6, v5
	v_fma_f32 v19, -v2, v18, v6
	v_fmac_f32_e32 v18, v19, v5
	v_fma_f32 v2, -v2, v18, v6
	v_div_fmas_f32 v2, v2, v5, v18
	v_mov_b32_e32 v5, v0
	v_pk_mul_f32 v[32:33], v[4:5], s[26:27] op_sel_hi:[1,0]
	v_div_fixup_f32 v30, v2, v1, 1.0
	v_fma_f32 v0, -v33, v33, v32
	v_max_f32_e32 v0, 0, v0
	v_add_f32_e32 v0, 0x358637bd, v0
	v_cmp_gt_f32_e32 vcc, s91, v0
	v_mul_f32_e32 v1, 0x4f800000, v0
	s_nop 0
	v_cndmask_b32_e32 v0, v0, v1, vcc
	v_sqrt_f32_e32 v1, v0
	s_nop 0
	v_add_u32_e32 v2, -1, v1
	v_fma_f32 v4, -v2, v1, v0
	v_cmp_ge_f32_e64 s[6:7], 0, v4
	v_add_u32_e32 v4, 1, v1
	s_nop 0
	v_cndmask_b32_e64 v2, v1, v2, s[6:7]
	v_fma_f32 v1, -v4, v1, v0
	v_cmp_lt_f32_e64 s[6:7], 0, v1
	s_nop 1
	v_cndmask_b32_e64 v1, v2, v4, s[6:7]
	v_mul_f32_e32 v2, 0x37800000, v1
	v_cndmask_b32_e32 v1, v1, v2, vcc
	v_cmp_class_f32_e32 vcc, v0, v254
	s_nop 1
	v_cndmask_b32_e32 v0, v1, v0, vcc
	v_div_scale_f32 v1, s[2:3], v0, v0, 1.0
	v_rcp_f32_e32 v2, v1
	s_nop 0
	v_fma_f32 v4, -v1, v2, 1.0
	v_fmac_f32_e32 v2, v4, v2
	v_div_scale_f32 v4, vcc, 1.0, v0, 1.0
	v_mul_f32_e32 v5, v4, v2
	v_fma_f32 v6, -v1, v5, v4
	v_fmac_f32_e32 v5, v6, v2
	v_fma_f32 v1, -v1, v5, v4
	v_div_fmas_f32 v1, v1, v2, v5
	v_div_fixup_f32 v32, v1, v0, 1.0
	v_mov_b32_e32 v0, v15
	v_mov_b32_e32 v1, v11
	v_pk_mul_f32 v[34:35], v[0:1], s[26:27] op_sel_hi:[1,0]
	v_mov_b32_e32 v15, v10
	v_fma_f32 v0, -v35, v35, v34
	v_max_f32_e32 v0, 0, v0
	v_add_f32_e32 v0, 0x358637bd, v0
	v_cmp_gt_f32_e32 vcc, s91, v0
	v_mul_f32_e32 v1, 0x4f800000, v0
	v_pk_mul_f32 v[36:37], v[14:15], s[26:27] op_sel_hi:[1,0]
	v_cndmask_b32_e32 v0, v0, v1, vcc
	v_sqrt_f32_e32 v1, v0
	s_nop 0
	v_add_u32_e32 v2, -1, v1
	v_fma_f32 v4, -v2, v1, v0
	v_cmp_ge_f32_e64 s[6:7], 0, v4
	v_add_u32_e32 v4, 1, v1
	s_nop 0
	v_cndmask_b32_e64 v2, v1, v2, s[6:7]
	v_fma_f32 v1, -v4, v1, v0
	v_cmp_lt_f32_e64 s[6:7], 0, v1
	s_nop 1
	v_cndmask_b32_e64 v1, v2, v4, s[6:7]
	v_mul_f32_e32 v2, 0x37800000, v1
	v_cndmask_b32_e32 v1, v1, v2, vcc
	v_cmp_class_f32_e32 vcc, v0, v254
	s_nop 1
	v_cndmask_b32_e32 v0, v1, v0, vcc
	v_div_scale_f32 v1, s[2:3], v0, v0, 1.0
	v_rcp_f32_e32 v2, v1
	s_nop 0
	v_fma_f32 v4, -v1, v2, 1.0
	v_fmac_f32_e32 v2, v4, v2
	v_div_scale_f32 v4, vcc, 1.0, v0, 1.0
	v_mul_f32_e32 v5, v4, v2
	v_fma_f32 v6, -v1, v5, v4
	v_fmac_f32_e32 v5, v6, v2
	v_fma_f32 v1, -v1, v5, v4
	v_div_fmas_f32 v1, v1, v2, v5
	v_div_fixup_f32 v34, v1, v0, 1.0
	v_fma_f32 v0, -v37, v37, v36
	v_max_f32_e32 v0, 0, v0
	v_add_f32_e32 v0, 0x358637bd, v0
	v_cmp_gt_f32_e32 vcc, s91, v0
	v_mul_f32_e32 v1, 0x4f800000, v0
	s_nop 0
	v_cndmask_b32_e32 v0, v0, v1, vcc
	v_sqrt_f32_e32 v1, v0
	s_nop 0
	v_add_u32_e32 v2, -1, v1
	v_fma_f32 v4, -v2, v1, v0
; __device__ __forceinline__ void gm_ln_block(bf16_t* Vt, const float* S1, const float* S2, const float* lng, const float* lnb, int c0, int t0, int tid) {
;     const int tt = t0 + (tid & 31) * 8, r0 = tid >> 5;
;     float mu[8], rs[8];
;     { const f32x4 a0 = *(const f32x4*)(S1 + tt), a1 = *(const f32x4*)(S1 + tt + 4), b0 = *(const f32x4*)(S2 + tt), b1 = *(const f32x4*)(S2 + tt + 4);
; #pragma unroll
;       for (int e = 0; e < 8; ++e) { const float s1 = e < 4 ? a0[e & 3] : a1[e & 3], s2 = e < 4 ? b0[e & 3] : b1[e & 3]; mu[e] = s1 * (1.f / GMH); rs[e] = 1.0f / sqrtf(fmaxf(s2 * (1.f / GMH) - mu[e] * mu[e], 0.f) + EPS); } }
; #pragma unroll
;     for (int k0 = 0; k0 < 16; k0 += 8) {
;         u32x4 raw[8];
; #pragma unroll
;         for (int k = 0; k < 8; ++k) raw[k] = *(const u32x4*)(Vt + (size_t)(c0 + r0 + 16 * (k0 + k)) * MALL + tt);
	v_cmp_ge_f32_e64 s[6:7], 0, v4
	v_add_u32_e32 v4, 1, v1
	s_nop 0
	v_cndmask_b32_e64 v2, v1, v2, s[6:7]
	v_fma_f32 v1, -v4, v1, v0
	v_cmp_lt_f32_e64 s[6:7], 0, v1
	s_nop 1
	v_cndmask_b32_e64 v1, v2, v4, s[6:7]
	v_mul_f32_e32 v2, 0x37800000, v1
	v_cndmask_b32_e32 v1, v1, v2, vcc
	v_cmp_class_f32_e32 vcc, v0, v254
	s_nop 1
	v_cndmask_b32_e32 v0, v1, v0, vcc
	v_div_scale_f32 v1, s[2:3], v0, v0, 1.0
	v_rcp_f32_e32 v2, v1
	s_nop 0
	v_fma_f32 v4, -v1, v2, 1.0
	v_fmac_f32_e32 v2, v4, v2
	v_div_scale_f32 v4, vcc, 1.0, v0, 1.0
	v_mul_f32_e32 v5, v4, v2
	v_fma_f32 v6, -v1, v5, v4
	v_fmac_f32_e32 v5, v6, v2
	v_fma_f32 v1, -v1, v5, v4
	v_div_fmas_f32 v1, v1, v2, v5
	v_div_fixup_f32 v36, v1, v0, 1.0
	v_mov_b32_e32 v0, v13
	v_mov_b32_e32 v1, v9
	v_pk_mul_f32 v[38:39], v[0:1], s[26:27] op_sel_hi:[1,0]
	v_mov_b32_e32 v13, v8
	v_fma_f32 v0, -v39, v39, v38
	v_max_f32_e32 v0, 0, v0
	v_add_f32_e32 v0, 0x358637bd, v0
	v_cmp_gt_f32_e32 vcc, s91, v0
	v_mul_f32_e32 v1, 0x4f800000, v0
	v_pk_mul_f32 v[40:41], v[12:13], s[26:27] op_sel_hi:[1,0]
	v_cndmask_b32_e32 v0, v0, v1, vcc
	v_sqrt_f32_e32 v1, v0
	s_nop 0
	v_add_u32_e32 v2, -1, v1
	v_fma_f32 v4, -v2, v1, v0
	v_cmp_ge_f32_e64 s[6:7], 0, v4
	v_add_u32_e32 v4, 1, v1
	s_nop 0
	v_cndmask_b32_e64 v2, v1, v2, s[6:7]
	v_fma_f32 v1, -v4, v1, v0
	v_cmp_lt_f32_e64 s[6:7], 0, v1
	s_nop 1
	v_cndmask_b32_e64 v1, v2, v4, s[6:7]
	v_mul_f32_e32 v2, 0x37800000, v1
	v_cndmask_b32_e32 v1, v1, v2, vcc
	v_cmp_class_f32_e32 vcc, v0, v254
	s_nop 1
	v_cndmask_b32_e32 v0, v1, v0, vcc
	v_div_scale_f32 v1, s[2:3], v0, v0, 1.0
	v_rcp_f32_e32 v2, v1
	s_nop 0
	v_fma_f32 v4, -v1, v2, 1.0
	v_fmac_f32_e32 v2, v4, v2
	v_div_scale_f32 v4, vcc, 1.0, v0, 1.0
	v_mul_f32_e32 v5, v4, v2
	v_fma_f32 v6, -v1, v5, v4
	v_fmac_f32_e32 v5, v6, v2
	v_fma_f32 v1, -v1, v5, v4
	v_div_fmas_f32 v1, v1, v2, v5
	v_div_fixup_f32 v38, v1, v0, 1.0
	v_fma_f32 v0, -v41, v41, v40
	v_max_f32_e32 v0, 0, v0
	v_add_f32_e32 v0, 0x358637bd, v0
	v_cmp_gt_f32_e32 vcc, s91, v0
	v_mul_f32_e32 v1, 0x4f800000, v0
	s_nop 0
	v_cndmask_b32_e32 v0, v0, v1, vcc
	v_sqrt_f32_e32 v1, v0
	s_nop 0
	v_add_u32_e32 v2, -1, v1
	v_fma_f32 v4, -v2, v1, v0
	v_cmp_ge_f32_e64 s[6:7], 0, v4
	v_add_u32_e32 v4, 1, v1
	s_nop 0
	v_cndmask_b32_e64 v2, v1, v2, s[6:7]
	v_fma_f32 v1, -v4, v1, v0
	v_cmp_lt_f32_e64 s[6:7], 0, v1
	s_nop 1
	v_cndmask_b32_e64 v1, v2, v4, s[6:7]
	v_mul_f32_e32 v2, 0x37800000, v1
	v_cndmask_b32_e32 v1, v1, v2, vcc
	v_cmp_class_f32_e32 vcc, v0, v254
	s_nop 1
	v_cndmask_b32_e32 v0, v1, v0, vcc
	v_div_scale_f32 v1, s[2:3], v0, v0, 1.0
	v_rcp_f32_e32 v2, v1
	s_nop 0
	v_fma_f32 v4, -v1, v2, 1.0
	v_fmac_f32_e32 v2, v4, v2
	v_div_scale_f32 v4, vcc, 1.0, v0, 1.0
	v_mul_f32_e32 v5, v4, v2
	v_fma_f32 v6, -v1, v5, v4
	v_fmac_f32_e32 v5, v6, v2
	v_fma_f32 v1, -v1, v5, v4
	v_div_fmas_f32 v1, v1, v2, v5
	v_mov_b32_e32 v2, v7
	v_pk_mul_f32 v[42:43], v[2:3], s[26:27] op_sel_hi:[1,0]
	v_div_fixup_f32 v40, v1, v0, 1.0
	v_fma_f32 v0, -v43, v43, v42
	v_max_f32_e32 v0, 0, v0
	v_add_f32_e32 v0, 0x358637bd, v0
	v_cmp_gt_f32_e32 vcc, s91, v0
	v_mul_f32_e32 v1, 0x4f800000, v0
	s_nop 0
	v_cndmask_b32_e32 v0, v0, v1, vcc
	v_sqrt_f32_e32 v1, v0
	s_nop 0
	v_add_u32_e32 v2, -1, v1
	v_fma_f32 v3, -v2, v1, v0
	v_cmp_ge_f32_e64 s[6:7], 0, v3
	v_add_u32_e32 v3, 1, v1
	s_nop 0
	v_cndmask_b32_e64 v2, v1, v2, s[6:7]
	v_fma_f32 v1, -v3, v1, v0
	v_cmp_lt_f32_e64 s[6:7], 0, v1
	s_nop 1
	v_cndmask_b32_e64 v1, v2, v3, s[6:7]
	s_mov_b32 s6, 0x8800
	v_mad_i64_i32 v[66:67], s[2:3], v52, s6, v[48:49]
	global_load_dwordx4 v[44:47], v[66:67], off
	v_mul_f32_e32 v2, 0x37800000, v1
	v_cndmask_b32_e32 v1, v1, v2, vcc
	v_cmp_class_f32_e32 vcc, v0, v254
	s_nop 1
	v_cndmask_b32_e32 v0, v1, v0, vcc
	v_div_scale_f32 v1, s[2:3], v0, v0, 1.0
	v_rcp_f32_e32 v2, v1
	s_nop 0
	v_fma_f32 v3, -v1, v2, 1.0
	v_fmac_f32_e32 v2, v3, v2
	v_div_scale_f32 v3, vcc, 1.0, v0, 1.0
	v_mul_f32_e32 v4, v3, v2
	v_fma_f32 v5, -v1, v4, v3
	v_fmac_f32_e32 v4, v5, v2
	v_fma_f32 v1, -v1, v4, v3
	v_div_fmas_f32 v1, v1, v2, v4
	v_div_fixup_f32 v42, v1, v0, 1.0
	v_add_u32_e32 v0, 16, v52
	v_mad_i64_i32 v[64:65], s[2:3], v0, s6, v[48:49]
	global_load_dwordx4 v[24:27], v[64:65], off
	v_add_u32_e32 v0, 32, v52
	v_mad_i64_i32 v[62:63], s[2:3], v0, s6, v[48:49]
	v_add_u32_e32 v0, 48, v52
	v_mad_i64_i32 v[60:61], s[2:3], v0, s6, v[48:49]
	v_add_u32_e32 v0, 64, v52
	v_mad_i64_i32 v[58:59], s[2:3], v0, s6, v[48:49]
	v_add_u32_e32 v0, 0x50, v52
	v_mad_i64_i32 v[56:57], s[2:3], v0, s6, v[48:49]
	v_add_u32_e32 v0, 0x60, v52
	v_mad_i64_i32 v[54:55], s[2:3], v0, s6, v[48:49]
	v_add_u32_e32 v0, 0x70, v52
	v_mad_i64_i32 v[50:51], s[2:3], v0, s6, v[48:49]
	global_load_dwordx4 v[20:23], v[62:63], off
	global_load_dwordx4 v[16:19], v[60:61], off
	global_load_dwordx4 v[12:15], v[58:59], off
	global_load_dwordx4 v[8:11], v[56:57], off
	global_load_dwordx4 v[4:7], v[54:55], off
	global_load_dwordx4 v[0:3], v[50:51], off
	s_mov_b64 s[2:3], 0x440000
	v_lshl_add_u64 v[132:133], v[66:67], 0, s[2:3]
	global_load_dwordx4 v[100:103], v[132:133], off
	v_lshl_add_u64 v[132:133], v[64:65], 0, s[2:3]
	global_load_dwordx4 v[104:107], v[132:133], off
	v_lshl_add_u64 v[132:133], v[62:63], 0, s[2:3]
	global_load_dwordx4 v[108:111], v[132:133], off
	v_lshl_add_u64 v[132:133], v[60:61], 0, s[2:3]
	global_load_dwordx4 v[112:115], v[132:133], off
	v_lshl_add_u64 v[132:133], v[58:59], 0, s[2:3]
	global_load_dwordx4 v[116:119], v[132:133], off
	v_lshl_add_u64 v[132:133], v[56:57], 0, s[2:3]
	global_load_dwordx4 v[120:123], v[132:133], off
	v_lshl_add_u64 v[132:133], v[54:55], 0, s[2:3]
	global_load_dwordx4 v[124:127], v[132:133], off
	v_lshl_add_u64 v[132:133], v[50:51], 0, s[2:3]
	global_load_dwordx4 v[128:131], v[132:133], off
	s_waitcnt vmcnt(15)
; __device__ __forceinline__ void unpack8(const u32x4 w, float* f) { f[0] = bf_lo(w.x); f[1] = bf_hi(w.x); f[2] = bf_lo(w.y); f[3] = bf_hi(w.y); f[4] = bf_lo(w.z); f[5] = bf_hi(w.z); f[6] = bf_lo(w.w); f[7] = bf_hi(w.w); }
; __device__ __forceinline__ u32x4 pack8(const float* f) { u32x4 w; w.x = cvt_pk_bf16(f[0], f[1]); w.y = cvt_pk_bf16(f[2], f[3]); w.z = cvt_pk_bf16(f[4], f[5]); w.w = cvt_pk_bf16(f[6], f[7]); return w; }
; __device__ __forceinline__ void gm_ln_block(bf16_t* Vt, const float* S1, const float* S2, const float* lng, const float* lnb, int c0, int t0, int tid) {
;     ...
;         for (int k = 0; k < 8; ++k) raw[k] = *(const u32x4*)(Vt + (size_t)(c0 + r0 + 16 * (k0 + k)) * MALL + tt);
; #pragma unroll
;         for (int k = 0; k < 8; ++k) { const int c = c0 + r0 + 16 * (k0 + k); float x[8]; unpack8(raw[k], x); const float g = lng[c], b = lnb[c];
; #pragma unroll
;             for (int e = 0; e < 8; ++e) x[e] = (x[e] - mu[e]) * (rs[e] * g) + b;
;             *(u32x4*)(Vt + (size_t)c * MALL + tt) = pack8(x); }
	v_lshlrev_b32_e32 v74, 16, v46
	v_and_b32_e32 v75, 0xffff0000, v46
	v_lshlrev_b32_e32 v76, 16, v47
	v_and_b32_e32 v77, 0xffff0000, v47
	v_lshlrev_b64 v[46:47], 2, v[52:53]
	v_lshlrev_b32_e32 v70, 16, v44
	v_and_b32_e32 v71, 0xffff0000, v44
	v_lshlrev_b32_e32 v72, 16, v45
	v_and_b32_e32 v73, 0xffff0000, v45
	v_lshl_add_u64 v[44:45], s[22:23], 0, v[46:47]
	global_load_dword v53, v[44:45], off
	v_lshl_add_u64 v[46:47], s[24:25], 0, v[46:47]
	global_load_dword v78, v[46:47], off
	global_load_dword v201, v[44:45], off offset:64
	global_load_dword v221, v[46:47], off offset:64
	global_load_dword v202, v[44:45], off offset:128
	global_load_dword v222, v[46:47], off offset:128
	global_load_dword v203, v[44:45], off offset:192
	global_load_dword v223, v[46:47], off offset:192
	global_load_dword v204, v[44:45], off offset:256
	global_load_dword v224, v[46:47], off offset:256
	global_load_dword v205, v[44:45], off offset:320
	global_load_dword v225, v[46:47], off offset:320
	global_load_dword v206, v[44:45], off offset:384
	global_load_dword v226, v[46:47], off offset:384
	global_load_dword v207, v[44:45], off offset:448
	global_load_dword v227, v[46:47], off offset:448
	global_load_dword v208, v[44:45], off offset:512
	global_load_dword v228, v[46:47], off offset:512
	global_load_dword v209, v[44:45], off offset:576
	global_load_dword v229, v[46:47], off offset:576
	global_load_dword v210, v[44:45], off offset:640
	global_load_dword v230, v[46:47], off offset:640
	global_load_dword v211, v[44:45], off offset:704
	global_load_dword v231, v[46:47], off offset:704
	global_load_dword v212, v[44:45], off offset:768
	global_load_dword v232, v[46:47], off offset:768
	global_load_dword v213, v[44:45], off offset:832
	global_load_dword v233, v[46:47], off offset:832
	global_load_dword v214, v[44:45], off offset:896
	global_load_dword v234, v[46:47], off offset:896
	global_load_dword v215, v[44:45], off offset:960
	global_load_dword v235, v[46:47], off offset:960
	v_sub_f32_e32 v70, v70, v41
	v_sub_f32_e32 v71, v71, v39
	v_sub_f32_e32 v72, v72, v37
	v_sub_f32_e32 v73, v73, v35
	v_sub_f32_e32 v74, v74, v33
	v_sub_f32_e32 v75, v75, v31
	v_sub_f32_e32 v76, v76, v29
	v_sub_f32_e32 v77, v77, v43
	s_waitcnt vmcnt(0)
	v_mul_f32_e32 v79, v40, v53
	v_fma_f32 v70, v70, v79, v78
	v_mul_f32_e32 v79, v38, v53
	v_fma_f32 v71, v71, v79, v78
	v_mul_f32_e32 v79, v36, v53
	v_fma_f32 v72, v72, v79, v78
	v_mul_f32_e32 v79, v34, v53
	v_fma_f32 v73, v73, v79, v78
	v_mul_f32_e32 v79, v32, v53
	v_fma_f32 v74, v74, v79, v78
	v_mul_f32_e32 v79, v30, v53
	v_fma_f32 v75, v75, v79, v78
	v_mul_f32_e32 v79, v28, v53
	v_mul_f32_e32 v53, v42, v53
	v_fma_f32 v76, v76, v79, v78
	v_fmac_f32_e32 v78, v77, v53
	v_cvt_pk_bf16_f32 v70, v70, v71
	v_cvt_pk_bf16_f32 v71, v72, v73
	v_cvt_pk_bf16_f32 v72, v74, v75
	v_cvt_pk_bf16_f32 v73, v76, v78
	global_store_dwordx4 v[66:67], v[70:73], off
	s_nop 2
	v_mov_b32_e32 v71, v201
	s_nop 0
	v_mov_b32_e32 v72, v221
	v_lshlrev_b32_e32 v53, 16, v24
	v_and_b32_e32 v24, 0xffff0000, v24
	v_sub_f32_e32 v53, v53, v41
	v_lshlrev_b32_e32 v66, 16, v25
	v_sub_f32_e32 v24, v24, v39
	v_and_b32_e32 v25, 0xffff0000, v25
	v_sub_f32_e32 v66, v66, v37
	v_lshlrev_b32_e32 v67, 16, v26
	v_sub_f32_e32 v25, v25, v35
	v_and_b32_e32 v26, 0xffff0000, v26
	v_sub_f32_e32 v67, v67, v33
	v_lshlrev_b32_e32 v70, 16, v27
	v_and_b32_e32 v27, 0xffff0000, v27
	v_sub_f32_e32 v26, v26, v31
	v_sub_f32_e32 v70, v70, v29
	v_sub_f32_e32 v27, v27, v43
	v_mul_f32_e32 v73, v40, v71
	v_fma_f32 v53, v53, v73, v72
	v_mul_f32_e32 v73, v38, v71
	v_fma_f32 v24, v24, v73, v72
	v_mul_f32_e32 v73, v36, v71
	v_fma_f32 v66, v66, v73, v72
	v_mul_f32_e32 v73, v34, v71
	v_fma_f32 v25, v25, v73, v72
	v_mul_f32_e32 v73, v32, v71
	v_fma_f32 v67, v67, v73, v72
	v_mul_f32_e32 v73, v30, v71
	v_fma_f32 v26, v26, v73, v72
	v_mul_f32_e32 v73, v28, v71
	v_mul_f32_e32 v71, v42, v71
	v_fma_f32 v70, v70, v73, v72
	v_fmac_f32_e32 v72, v27, v71
	v_cvt_pk_bf16_f32 v24, v53, v24
	v_cvt_pk_bf16_f32 v25, v66, v25
	v_cvt_pk_bf16_f32 v26, v67, v26
	v_cvt_pk_bf16_f32 v27, v70, v72
	global_store_dwordx4 v[64:65], v[24:27], off
	s_nop 2
	v_mov_b32_e32 v53, v202
	s_nop 0
	v_mov_b32_e32 v64, v222
	v_lshlrev_b32_e32 v24, 16, v20
	v_and_b32_e32 v20, 0xffff0000, v20
	v_sub_f32_e32 v24, v24, v41
	v_lshlrev_b32_e32 v25, 16, v21
	v_sub_f32_e32 v20, v20, v39
	v_and_b32_e32 v21, 0xffff0000, v21
	v_sub_f32_e32 v25, v25, v37
	v_lshlrev_b32_e32 v26, 16, v22
	v_sub_f32_e32 v21, v21, v35
	v_and_b32_e32 v22, 0xffff0000, v22
	v_sub_f32_e32 v26, v26, v33
	v_lshlrev_b32_e32 v27, 16, v23
	v_and_b32_e32 v23, 0xffff0000, v23
	v_sub_f32_e32 v22, v22, v31
	v_sub_f32_e32 v27, v27, v29
	v_sub_f32_e32 v23, v23, v43
	v_mul_f32_e32 v65, v40, v53
	v_fma_f32 v24, v24, v65, v64
	v_mul_f32_e32 v65, v38, v53
	v_fma_f32 v20, v20, v65, v64
	v_mul_f32_e32 v65, v36, v53
	v_fma_f32 v25, v25, v65, v64
	v_mul_f32_e32 v65, v34, v53
	v_fma_f32 v21, v21, v65, v64
	v_mul_f32_e32 v65, v32, v53
	v_fma_f32 v26, v26, v65, v64
	v_mul_f32_e32 v65, v30, v53
	v_fma_f32 v22, v22, v65, v64
	v_mul_f32_e32 v65, v28, v53
	v_mul_f32_e32 v53, v42, v53
	v_fma_f32 v27, v27, v65, v64
	v_fmac_f32_e32 v64, v23, v53
	v_cvt_pk_bf16_f32 v20, v24, v20
	v_cvt_pk_bf16_f32 v21, v25, v21
	v_cvt_pk_bf16_f32 v22, v26, v22
	v_cvt_pk_bf16_f32 v23, v27, v64
	global_store_dwordx4 v[62:63], v[20:23], off
	s_nop 2
	v_mov_b32_e32 v24, v203
	v_mov_b32_e32 v25, v223
	v_lshlrev_b32_e32 v20, 16, v16
	v_and_b32_e32 v16, 0xffff0000, v16
	v_sub_f32_e32 v20, v20, v41
	v_lshlrev_b32_e32 v21, 16, v17
	v_sub_f32_e32 v16, v16, v39
	v_and_b32_e32 v17, 0xffff0000, v17
	v_sub_f32_e32 v21, v21, v37
	v_lshlrev_b32_e32 v22, 16, v18
; __device__ __forceinline__ void unpack8(const u32x4 w, float* f) { f[0] = bf_lo(w.x); f[1] = bf_hi(w.x); f[2] = bf_lo(w.y); f[3] = bf_hi(w.y); f[4] = bf_lo(w.z); f[5] = bf_hi(w.z); f[6] = bf_lo(w.w); f[7] = bf_hi(w.w); }
; __device__ __forceinline__ u32x4 pack8(const float* f) { u32x4 w; w.x = cvt_pk_bf16(f[0], f[1]); w.y = cvt_pk_bf16(f[2], f[3]); w.z = cvt_pk_bf16(f[4], f[5]); w.w = cvt_pk_bf16(f[6], f[7]); return w; }
; __device__ __forceinline__ void gm_ln_block(bf16_t* Vt, const float* S1, const float* S2, const float* lng, const float* lnb, int c0, int t0, int tid) {
;     ...
;         for (int k = 0; k < 8; ++k) { const int c = c0 + r0 + 16 * (k0 + k); float x[8]; unpack8(raw[k], x); const float g = lng[c], b = lnb[c];
; #pragma unroll
;             for (int e = 0; e < 8; ++e) x[e] = (x[e] - mu[e]) * (rs[e] * g) + b;
;             *(u32x4*)(Vt + (size_t)c * MALL + tt) = pack8(x); }
	v_sub_f32_e32 v17, v17, v35
	v_and_b32_e32 v18, 0xffff0000, v18
	v_sub_f32_e32 v22, v22, v33
	v_lshlrev_b32_e32 v23, 16, v19
	v_and_b32_e32 v19, 0xffff0000, v19
	v_sub_f32_e32 v18, v18, v31
	v_sub_f32_e32 v23, v23, v29
	v_sub_f32_e32 v19, v19, v43
	v_mul_f32_e32 v26, v40, v24
	v_fma_f32 v20, v20, v26, v25
	v_mul_f32_e32 v26, v38, v24
	v_fma_f32 v16, v16, v26, v25
	v_mul_f32_e32 v26, v36, v24
	v_fma_f32 v21, v21, v26, v25
	v_mul_f32_e32 v26, v34, v24
	v_fma_f32 v17, v17, v26, v25
	v_mul_f32_e32 v26, v32, v24
	v_fma_f32 v22, v22, v26, v25
	v_mul_f32_e32 v26, v30, v24
	v_fma_f32 v18, v18, v26, v25
	v_mul_f32_e32 v26, v28, v24
	v_mul_f32_e32 v24, v42, v24
	v_fma_f32 v23, v23, v26, v25
	v_fmac_f32_e32 v25, v19, v24
	v_cvt_pk_bf16_f32 v16, v20, v16
	v_cvt_pk_bf16_f32 v17, v21, v17
	v_cvt_pk_bf16_f32 v18, v22, v18
	v_cvt_pk_bf16_f32 v19, v23, v25
	global_store_dwordx4 v[60:61], v[16:19], off
	s_nop 2
	v_mov_b32_e32 v20, v204
	v_mov_b32_e32 v21, v224
	v_lshlrev_b32_e32 v16, 16, v12
	v_and_b32_e32 v12, 0xffff0000, v12
	v_sub_f32_e32 v16, v16, v41
	v_lshlrev_b32_e32 v17, 16, v13
	v_sub_f32_e32 v12, v12, v39
	v_and_b32_e32 v13, 0xffff0000, v13
	v_sub_f32_e32 v17, v17, v37
	v_lshlrev_b32_e32 v18, 16, v14
	v_sub_f32_e32 v13, v13, v35
	v_and_b32_e32 v14, 0xffff0000, v14
	v_sub_f32_e32 v18, v18, v33
	v_lshlrev_b32_e32 v19, 16, v15
	v_and_b32_e32 v15, 0xffff0000, v15
	v_sub_f32_e32 v14, v14, v31
	v_sub_f32_e32 v19, v19, v29
	v_sub_f32_e32 v15, v15, v43
	v_mul_f32_e32 v22, v40, v20
	v_fma_f32 v16, v16, v22, v21
	v_mul_f32_e32 v22, v38, v20
	v_fma_f32 v12, v12, v22, v21
	v_mul_f32_e32 v22, v36, v20
	v_fma_f32 v17, v17, v22, v21
	v_mul_f32_e32 v22, v34, v20
	v_fma_f32 v13, v13, v22, v21
	v_mul_f32_e32 v22, v32, v20
	v_fma_f32 v18, v18, v22, v21
	v_mul_f32_e32 v22, v30, v20
	v_fma_f32 v14, v14, v22, v21
	v_mul_f32_e32 v22, v28, v20
	v_mul_f32_e32 v20, v42, v20
	v_fma_f32 v19, v19, v22, v21
	v_fmac_f32_e32 v21, v15, v20
	v_cvt_pk_bf16_f32 v12, v16, v12
	v_cvt_pk_bf16_f32 v13, v17, v13
	v_cvt_pk_bf16_f32 v14, v18, v14
	v_cvt_pk_bf16_f32 v15, v19, v21
	global_store_dwordx4 v[58:59], v[12:15], off
	s_nop 2
	v_mov_b32_e32 v16, v205
	v_mov_b32_e32 v17, v225
	v_lshlrev_b32_e32 v12, 16, v8
	v_and_b32_e32 v8, 0xffff0000, v8
	v_sub_f32_e32 v12, v12, v41
	v_lshlrev_b32_e32 v13, 16, v9
	v_sub_f32_e32 v8, v8, v39
	v_and_b32_e32 v9, 0xffff0000, v9
	v_sub_f32_e32 v13, v13, v37
	v_lshlrev_b32_e32 v14, 16, v10
	v_sub_f32_e32 v9, v9, v35
	v_and_b32_e32 v10, 0xffff0000, v10
	v_sub_f32_e32 v14, v14, v33
	v_lshlrev_b32_e32 v15, 16, v11
	v_and_b32_e32 v11, 0xffff0000, v11
	v_sub_f32_e32 v10, v10, v31
	v_sub_f32_e32 v15, v15, v29
	v_sub_f32_e32 v11, v11, v43
	v_mul_f32_e32 v18, v40, v16
	v_fma_f32 v12, v12, v18, v17
	v_mul_f32_e32 v18, v38, v16
	v_fma_f32 v8, v8, v18, v17
	v_mul_f32_e32 v18, v36, v16
	v_fma_f32 v13, v13, v18, v17
	v_mul_f32_e32 v18, v34, v16
	v_fma_f32 v9, v9, v18, v17
	v_mul_f32_e32 v18, v32, v16
	v_fma_f32 v14, v14, v18, v17
	v_mul_f32_e32 v18, v30, v16
	v_fma_f32 v10, v10, v18, v17
	v_mul_f32_e32 v18, v28, v16
	v_mul_f32_e32 v16, v42, v16
	v_fma_f32 v15, v15, v18, v17
	v_fmac_f32_e32 v17, v11, v16
	v_cvt_pk_bf16_f32 v8, v12, v8
	v_cvt_pk_bf16_f32 v9, v13, v9
	v_cvt_pk_bf16_f32 v10, v14, v10
	v_cvt_pk_bf16_f32 v11, v15, v17
	global_store_dwordx4 v[56:57], v[8:11], off
	s_nop 2
	v_mov_b32_e32 v12, v206
	v_mov_b32_e32 v13, v226
	v_lshlrev_b32_e32 v8, 16, v4
	v_and_b32_e32 v4, 0xffff0000, v4
	v_sub_f32_e32 v8, v8, v41
	v_lshlrev_b32_e32 v9, 16, v5
	v_sub_f32_e32 v4, v4, v39
	v_and_b32_e32 v5, 0xffff0000, v5
	v_sub_f32_e32 v9, v9, v37
	v_lshlrev_b32_e32 v10, 16, v6
	v_sub_f32_e32 v5, v5, v35
	v_and_b32_e32 v6, 0xffff0000, v6
	v_sub_f32_e32 v10, v10, v33
	v_lshlrev_b32_e32 v11, 16, v7
	v_and_b32_e32 v7, 0xffff0000, v7
	v_sub_f32_e32 v6, v6, v31
	v_sub_f32_e32 v11, v11, v29
	v_sub_f32_e32 v7, v7, v43
	v_mul_f32_e32 v14, v40, v12
	v_fma_f32 v8, v8, v14, v13
	v_mul_f32_e32 v14, v38, v12
	v_fma_f32 v4, v4, v14, v13
	v_mul_f32_e32 v14, v36, v12
	v_fma_f32 v9, v9, v14, v13
	v_mul_f32_e32 v14, v34, v12
	v_fma_f32 v5, v5, v14, v13
	v_mul_f32_e32 v14, v32, v12
	v_fma_f32 v10, v10, v14, v13
	v_mul_f32_e32 v14, v30, v12
	v_fma_f32 v6, v6, v14, v13
	v_mul_f32_e32 v14, v28, v12
	v_mul_f32_e32 v12, v42, v12
	v_fma_f32 v11, v11, v14, v13
	v_fmac_f32_e32 v13, v7, v12
	v_cvt_pk_bf16_f32 v4, v8, v4
	v_cvt_pk_bf16_f32 v5, v9, v5
	v_cvt_pk_bf16_f32 v6, v10, v6
	v_cvt_pk_bf16_f32 v7, v11, v13
	global_store_dwordx4 v[54:55], v[4:7], off
	s_nop 2
	v_mov_b32_e32 v8, v207
	v_mov_b32_e32 v9, v227
	v_lshlrev_b32_e32 v4, 16, v0
	v_and_b32_e32 v0, 0xffff0000, v0
	v_sub_f32_e32 v4, v4, v41
	v_lshlrev_b32_e32 v5, 16, v1
	v_sub_f32_e32 v0, v0, v39
	v_and_b32_e32 v1, 0xffff0000, v1
	v_sub_f32_e32 v5, v5, v37
	v_lshlrev_b32_e32 v6, 16, v2
	v_sub_f32_e32 v1, v1, v35
	v_and_b32_e32 v2, 0xffff0000, v2
	v_sub_f32_e32 v6, v6, v33
	v_lshlrev_b32_e32 v7, 16, v3
	v_and_b32_e32 v3, 0xffff0000, v3
	v_sub_f32_e32 v2, v2, v31
	v_sub_f32_e32 v7, v7, v29
	v_sub_f32_e32 v3, v3, v43
	v_mul_f32_e32 v10, v40, v8
	v_fma_f32 v4, v4, v10, v9
	v_mul_f32_e32 v10, v38, v8
	v_fma_f32 v0, v0, v10, v9
	v_mul_f32_e32 v10, v36, v8
	v_fma_f32 v5, v5, v10, v9
	v_mul_f32_e32 v10, v34, v8
	v_fma_f32 v1, v1, v10, v9
	v_mul_f32_e32 v10, v32, v8
	v_fma_f32 v6, v6, v10, v9
	v_mul_f32_e32 v10, v30, v8
	v_fma_f32 v2, v2, v10, v9
	v_mul_f32_e32 v10, v28, v8
	v_mul_f32_e32 v8, v42, v8
	v_cvt_pk_bf16_f32 v0, v4, v0
	v_fma_f32 v7, v7, v10, v9
	v_fmac_f32_e32 v9, v3, v8
	v_cvt_pk_bf16_f32 v1, v5, v1
	v_cvt_pk_bf16_f32 v2, v6, v2
	v_cvt_pk_bf16_f32 v3, v7, v9
	global_store_dwordx4 v[50:51], v[0:3], off
	s_nop 1
	v_add_u32_e32 v0, 0x80, v52
; __device__ __forceinline__ void unpack8(const u32x4 w, float* f) { f[0] = bf_lo(w.x); f[1] = bf_hi(w.x); f[2] = bf_lo(w.y); f[3] = bf_hi(w.y); f[4] = bf_lo(w.z); f[5] = bf_hi(w.z); f[6] = bf_lo(w.w); f[7] = bf_hi(w.w); }
; __device__ __forceinline__ u32x4 pack8(const float* f) { u32x4 w; w.x = cvt_pk_bf16(f[0], f[1]); w.y = cvt_pk_bf16(f[2], f[3]); w.z = cvt_pk_bf16(f[4], f[5]); w.w = cvt_pk_bf16(f[6], f[7]); return w; }
; __device__ __forceinline__ void gm_ln_block(bf16_t* Vt, const float* S1, const float* S2, const float* lng, const float* lnb, int c0, int t0, int tid) {
;     ...
;     for (int k0 = 0; k0 < 16; k0 += 8) {
;         u32x4 raw[8];
; #pragma unroll
;         for (int k = 0; k < 8; ++k) raw[k] = *(const u32x4*)(Vt + (size_t)(c0 + r0 + 16 * (k0 + k)) * MALL + tt);
; #pragma unroll
;         for (int k = 0; k < 8; ++k) { const int c = c0 + r0 + 16 * (k0 + k); float x[8]; unpack8(raw[k], x); const float g = lng[c], b = lnb[c];
; #pragma unroll
;             for (int e = 0; e < 8; ++e) x[e] = (x[e] - mu[e]) * (rs[e] * g) + b;
;             *(u32x4*)(Vt + (size_t)c * MALL + tt) = pack8(x); }
	v_mad_i64_i32 v[64:65], s[2:3], v0, s6, v[48:49]
	v_add_u32_e32 v0, 0x90, v52
	v_mad_i64_i32 v[62:63], s[2:3], v0, s6, v[48:49]
	v_add_u32_e32 v0, 0xa0, v52
	v_mad_i64_i32 v[60:61], s[2:3], v0, s6, v[48:49]
	v_add_u32_e32 v0, 0xb0, v52
	v_mad_i64_i32 v[58:59], s[2:3], v0, s6, v[48:49]
	v_add_u32_e32 v0, 0xc0, v52
	v_mad_i64_i32 v[56:57], s[2:3], v0, s6, v[48:49]
	v_add_u32_e32 v0, 0xd0, v52
	v_mad_i64_i32 v[54:55], s[2:3], v0, s6, v[48:49]
	v_add_u32_e32 v0, 0xe0, v52
	s_nop 2
	v_mov_b32_e32 v70, v100
	v_mov_b32_e32 v71, v101
	v_mov_b32_e32 v72, v102
	v_mov_b32_e32 v73, v103
	v_mov_b32_e32 v24, v104
	v_mov_b32_e32 v25, v105
	v_mov_b32_e32 v26, v106
	v_mov_b32_e32 v27, v107
	v_mad_i64_i32 v[50:51], s[2:3], v0, s6, v[48:49]
	v_add_u32_e32 v0, 0xf0, v52
	v_mad_i64_i32 v[48:49], s[2:3], v0, s6, v[48:49]
	v_mov_b32_e32 v20, v108
	v_mov_b32_e32 v21, v109
	v_mov_b32_e32 v22, v110
	v_mov_b32_e32 v23, v111
	v_mov_b32_e32 v16, v112
	v_mov_b32_e32 v17, v113
	v_mov_b32_e32 v18, v114
	v_mov_b32_e32 v19, v115
	v_mov_b32_e32 v12, v116
	v_mov_b32_e32 v13, v117
	v_mov_b32_e32 v14, v118
	v_mov_b32_e32 v15, v119
	v_mov_b32_e32 v8, v120
	v_mov_b32_e32 v9, v121
	v_mov_b32_e32 v10, v122
	v_mov_b32_e32 v11, v123
	v_mov_b32_e32 v4, v124
	v_mov_b32_e32 v5, v125
	v_mov_b32_e32 v6, v126
	v_mov_b32_e32 v7, v127
	v_mov_b32_e32 v0, v128
	v_mov_b32_e32 v1, v129
	v_mov_b32_e32 v2, v130
	v_mov_b32_e32 v3, v131
	s_nop 2
	v_mov_b32_e32 v74, v208
	v_mov_b32_e32 v75, v228
	s_mov_b64 s[6:7], 0
	v_lshlrev_b32_e32 v52, 16, v70
	v_and_b32_e32 v53, 0xffff0000, v70
	v_sub_f32_e32 v52, v52, v41
	v_lshlrev_b32_e32 v66, 16, v71
	v_sub_f32_e32 v53, v53, v39
	v_and_b32_e32 v67, 0xffff0000, v71
	v_sub_f32_e32 v66, v66, v37
	v_lshlrev_b32_e32 v70, 16, v72
	v_sub_f32_e32 v67, v67, v35
	v_and_b32_e32 v71, 0xffff0000, v72
	v_sub_f32_e32 v70, v70, v33
	v_lshlrev_b32_e32 v72, 16, v73
	v_mul_f32_e32 v76, v40, v74
	v_fma_f32 v52, v52, v76, v75
	v_mul_f32_e32 v76, v38, v74
	v_fma_f32 v53, v53, v76, v75
	v_mul_f32_e32 v76, v36, v74
	v_fma_f32 v66, v66, v76, v75
	v_mul_f32_e32 v76, v34, v74
	v_fma_f32 v67, v67, v76, v75
	v_mul_f32_e32 v76, v32, v74
	v_fma_f32 v76, v70, v76, v75
	v_sub_f32_e32 v70, v71, v31
	v_mul_f32_e32 v71, v30, v74
	v_and_b32_e32 v73, 0xffff0000, v73
	v_fma_f32 v77, v70, v71, v75
	v_sub_f32_e32 v70, v72, v29
	v_mul_f32_e32 v71, v28, v74
	v_fma_f32 v78, v70, v71, v75
	v_sub_f32_e32 v70, v73, v43
	v_mul_f32_e32 v71, v42, v74
	v_fmac_f32_e32 v75, v70, v71
	v_cvt_pk_bf16_f32 v70, v52, v53
	v_cvt_pk_bf16_f32 v71, v66, v67
	v_cvt_pk_bf16_f32 v72, v76, v77
	v_cvt_pk_bf16_f32 v73, v78, v75
	global_store_dwordx4 v[64:65], v[70:73], off
	s_nop 2
	v_mov_b32_e32 v66, v209
	v_mov_b32_e32 v67, v229
	v_lshlrev_b32_e32 v52, 16, v24
	v_and_b32_e32 v24, 0xffff0000, v24
	v_sub_f32_e32 v52, v52, v41
	v_lshlrev_b32_e32 v53, 16, v25
	v_sub_f32_e32 v24, v24, v39
	v_and_b32_e32 v25, 0xffff0000, v25
	v_sub_f32_e32 v53, v53, v37
	v_lshlrev_b32_e32 v64, 16, v26
	v_sub_f32_e32 v25, v25, v35
	v_and_b32_e32 v26, 0xffff0000, v26
	v_sub_f32_e32 v64, v64, v33
	v_lshlrev_b32_e32 v65, 16, v27
	v_and_b32_e32 v27, 0xffff0000, v27
	v_sub_f32_e32 v26, v26, v31
	v_sub_f32_e32 v65, v65, v29
	v_sub_f32_e32 v27, v27, v43
	v_mul_f32_e32 v70, v40, v66
	v_fma_f32 v52, v52, v70, v67
	v_mul_f32_e32 v70, v38, v66
	v_fma_f32 v24, v24, v70, v67
	v_mul_f32_e32 v70, v36, v66
	v_fma_f32 v53, v53, v70, v67
	v_mul_f32_e32 v70, v34, v66
	v_fma_f32 v25, v25, v70, v67
	v_mul_f32_e32 v70, v32, v66
	v_fma_f32 v64, v64, v70, v67
	v_mul_f32_e32 v70, v30, v66
	v_fma_f32 v26, v26, v70, v67
	v_mul_f32_e32 v70, v28, v66
	v_mul_f32_e32 v66, v42, v66
	v_fma_f32 v65, v65, v70, v67
	v_fmac_f32_e32 v67, v27, v66
	v_cvt_pk_bf16_f32 v24, v52, v24
	v_cvt_pk_bf16_f32 v25, v53, v25
	v_cvt_pk_bf16_f32 v26, v64, v26
	v_cvt_pk_bf16_f32 v27, v65, v67
	global_store_dwordx4 v[62:63], v[24:27], off
	s_nop 2
	v_mov_b32_e32 v52, v210
	v_mov_b32_e32 v53, v230
	v_lshlrev_b32_e32 v24, 16, v20
	v_and_b32_e32 v20, 0xffff0000, v20
	v_sub_f32_e32 v24, v24, v41
	v_lshlrev_b32_e32 v25, 16, v21
	v_sub_f32_e32 v20, v20, v39
	v_and_b32_e32 v21, 0xffff0000, v21
	v_sub_f32_e32 v25, v25, v37
	v_lshlrev_b32_e32 v26, 16, v22
	v_sub_f32_e32 v21, v21, v35
	v_and_b32_e32 v22, 0xffff0000, v22
	v_sub_f32_e32 v26, v26, v33
	v_lshlrev_b32_e32 v27, 16, v23
	v_and_b32_e32 v23, 0xffff0000, v23
	v_sub_f32_e32 v22, v22, v31
	v_sub_f32_e32 v27, v27, v29
	v_sub_f32_e32 v23, v23, v43
	v_mul_f32_e32 v62, v40, v52
	v_fma_f32 v24, v24, v62, v53
	v_mul_f32_e32 v62, v38, v52
	v_fma_f32 v20, v20, v62, v53
	v_mul_f32_e32 v62, v36, v52
	v_fma_f32 v25, v25, v62, v53
	v_mul_f32_e32 v62, v34, v52
	v_fma_f32 v21, v21, v62, v53
	v_mul_f32_e32 v62, v32, v52
	v_fma_f32 v26, v26, v62, v53
	v_mul_f32_e32 v62, v30, v52
	v_fma_f32 v22, v22, v62, v53
	v_mul_f32_e32 v62, v28, v52
	v_mul_f32_e32 v52, v42, v52
	v_fma_f32 v27, v27, v62, v53
	v_fmac_f32_e32 v53, v23, v52
	v_cvt_pk_bf16_f32 v20, v24, v20
	v_cvt_pk_bf16_f32 v21, v25, v21
	v_cvt_pk_bf16_f32 v22, v26, v22
	v_cvt_pk_bf16_f32 v23, v27, v53
	global_store_dwordx4 v[60:61], v[20:23], off
	s_nop 2
	v_mov_b32_e32 v24, v211
	v_mov_b32_e32 v25, v231
	v_lshlrev_b32_e32 v20, 16, v16
	v_and_b32_e32 v16, 0xffff0000, v16
	v_sub_f32_e32 v20, v20, v41
	v_lshlrev_b32_e32 v21, 16, v17
	v_sub_f32_e32 v16, v16, v39
	v_and_b32_e32 v17, 0xffff0000, v17
	v_sub_f32_e32 v21, v21, v37
	v_lshlrev_b32_e32 v22, 16, v18
	v_sub_f32_e32 v17, v17, v35
	v_and_b32_e32 v18, 0xffff0000, v18
	v_sub_f32_e32 v22, v22, v33
	v_lshlrev_b32_e32 v23, 16, v19
; __device__ __forceinline__ void unpack8(const u32x4 w, float* f) { f[0] = bf_lo(w.x); f[1] = bf_hi(w.x); f[2] = bf_lo(w.y); f[3] = bf_hi(w.y); f[4] = bf_lo(w.z); f[5] = bf_hi(w.z); f[6] = bf_lo(w.w); f[7] = bf_hi(w.w); }
; __device__ __forceinline__ u32x4 pack8(const float* f) { u32x4 w; w.x = cvt_pk_bf16(f[0], f[1]); w.y = cvt_pk_bf16(f[2], f[3]); w.z = cvt_pk_bf16(f[4], f[5]); w.w = cvt_pk_bf16(f[6], f[7]); return w; }
; __device__ __forceinline__ void gm_ln_block(bf16_t* Vt, const float* S1, const float* S2, const float* lng, const float* lnb, int c0, int t0, int tid) {
;     ...
;         for (int k = 0; k < 8; ++k) { const int c = c0 + r0 + 16 * (k0 + k); float x[8]; unpack8(raw[k], x); const float g = lng[c], b = lnb[c];
; #pragma unroll
;             for (int e = 0; e < 8; ++e) x[e] = (x[e] - mu[e]) * (rs[e] * g) + b;
;             *(u32x4*)(Vt + (size_t)c * MALL + tt) = pack8(x); }
	v_and_b32_e32 v19, 0xffff0000, v19
	v_sub_f32_e32 v18, v18, v31
	v_sub_f32_e32 v23, v23, v29
	v_sub_f32_e32 v19, v19, v43
	v_mul_f32_e32 v26, v40, v24
	v_fma_f32 v20, v20, v26, v25
	v_mul_f32_e32 v26, v38, v24
	v_fma_f32 v16, v16, v26, v25
	v_mul_f32_e32 v26, v36, v24
	v_fma_f32 v21, v21, v26, v25
	v_mul_f32_e32 v26, v34, v24
	v_fma_f32 v17, v17, v26, v25
	v_mul_f32_e32 v26, v32, v24
	v_fma_f32 v22, v22, v26, v25
	v_mul_f32_e32 v26, v30, v24
	v_fma_f32 v18, v18, v26, v25
	v_mul_f32_e32 v26, v28, v24
	v_mul_f32_e32 v24, v42, v24
	v_fma_f32 v23, v23, v26, v25
	v_fmac_f32_e32 v25, v19, v24
	v_cvt_pk_bf16_f32 v16, v20, v16
	v_cvt_pk_bf16_f32 v17, v21, v17
	v_cvt_pk_bf16_f32 v18, v22, v18
	v_cvt_pk_bf16_f32 v19, v23, v25
	global_store_dwordx4 v[58:59], v[16:19], off
	s_nop 2
	v_mov_b32_e32 v20, v212
	v_mov_b32_e32 v21, v232
	v_lshlrev_b32_e32 v16, 16, v12
	v_and_b32_e32 v12, 0xffff0000, v12
	v_sub_f32_e32 v16, v16, v41
	v_lshlrev_b32_e32 v17, 16, v13
	v_sub_f32_e32 v12, v12, v39
	v_and_b32_e32 v13, 0xffff0000, v13
	v_sub_f32_e32 v17, v17, v37
	v_lshlrev_b32_e32 v18, 16, v14
	v_sub_f32_e32 v13, v13, v35
	v_and_b32_e32 v14, 0xffff0000, v14
	v_sub_f32_e32 v18, v18, v33
	v_lshlrev_b32_e32 v19, 16, v15
	v_and_b32_e32 v15, 0xffff0000, v15
	v_sub_f32_e32 v14, v14, v31
	v_sub_f32_e32 v19, v19, v29
	v_sub_f32_e32 v15, v15, v43
	v_mul_f32_e32 v22, v40, v20
	v_fma_f32 v16, v16, v22, v21
	v_mul_f32_e32 v22, v38, v20
	v_fma_f32 v12, v12, v22, v21
	v_mul_f32_e32 v22, v36, v20
	v_fma_f32 v17, v17, v22, v21
	v_mul_f32_e32 v22, v34, v20
	v_fma_f32 v13, v13, v22, v21
	v_mul_f32_e32 v22, v32, v20
	v_fma_f32 v18, v18, v22, v21
	v_mul_f32_e32 v22, v30, v20
	v_fma_f32 v14, v14, v22, v21
	v_mul_f32_e32 v22, v28, v20
	v_mul_f32_e32 v20, v42, v20
	v_fma_f32 v19, v19, v22, v21
	v_fmac_f32_e32 v21, v15, v20
	v_cvt_pk_bf16_f32 v12, v16, v12
	v_cvt_pk_bf16_f32 v13, v17, v13
	v_cvt_pk_bf16_f32 v14, v18, v14
	v_cvt_pk_bf16_f32 v15, v19, v21
	global_store_dwordx4 v[56:57], v[12:15], off
	s_nop 2
	v_mov_b32_e32 v16, v213
	v_mov_b32_e32 v17, v233
	v_lshlrev_b32_e32 v12, 16, v8
	v_and_b32_e32 v8, 0xffff0000, v8
	v_sub_f32_e32 v12, v12, v41
	v_lshlrev_b32_e32 v13, 16, v9
	v_sub_f32_e32 v8, v8, v39
	v_and_b32_e32 v9, 0xffff0000, v9
	v_sub_f32_e32 v13, v13, v37
	v_lshlrev_b32_e32 v14, 16, v10
	v_sub_f32_e32 v9, v9, v35
	v_and_b32_e32 v10, 0xffff0000, v10
	v_sub_f32_e32 v14, v14, v33
	v_lshlrev_b32_e32 v15, 16, v11
	v_and_b32_e32 v11, 0xffff0000, v11
	v_sub_f32_e32 v10, v10, v31
	v_sub_f32_e32 v15, v15, v29
	v_sub_f32_e32 v11, v11, v43
	v_mul_f32_e32 v18, v40, v16
	v_fma_f32 v12, v12, v18, v17
	v_mul_f32_e32 v18, v38, v16
	v_fma_f32 v8, v8, v18, v17
	v_mul_f32_e32 v18, v36, v16
	v_fma_f32 v13, v13, v18, v17
	v_mul_f32_e32 v18, v34, v16
	v_fma_f32 v9, v9, v18, v17
	v_mul_f32_e32 v18, v32, v16
	v_fma_f32 v14, v14, v18, v17
	v_mul_f32_e32 v18, v30, v16
	v_fma_f32 v10, v10, v18, v17
	v_mul_f32_e32 v18, v28, v16
	v_mul_f32_e32 v16, v42, v16
	v_fma_f32 v15, v15, v18, v17
	v_fmac_f32_e32 v17, v11, v16
	v_cvt_pk_bf16_f32 v8, v12, v8
	v_cvt_pk_bf16_f32 v9, v13, v9
	v_cvt_pk_bf16_f32 v10, v14, v10
	v_cvt_pk_bf16_f32 v11, v15, v17
	global_store_dwordx4 v[54:55], v[8:11], off
	s_nop 2
	v_mov_b32_e32 v12, v214
	v_mov_b32_e32 v13, v234
	v_lshlrev_b32_e32 v8, 16, v4
	v_and_b32_e32 v4, 0xffff0000, v4
	v_sub_f32_e32 v8, v8, v41
	v_lshlrev_b32_e32 v9, 16, v5
	v_sub_f32_e32 v4, v4, v39
	v_and_b32_e32 v5, 0xffff0000, v5
	v_sub_f32_e32 v9, v9, v37
	v_lshlrev_b32_e32 v10, 16, v6
	v_sub_f32_e32 v5, v5, v35
	v_and_b32_e32 v6, 0xffff0000, v6
	v_sub_f32_e32 v10, v10, v33
	v_lshlrev_b32_e32 v11, 16, v7
	v_and_b32_e32 v7, 0xffff0000, v7
	v_sub_f32_e32 v6, v6, v31
	v_sub_f32_e32 v11, v11, v29
	v_sub_f32_e32 v7, v7, v43
	v_mul_f32_e32 v14, v40, v12
	v_fma_f32 v8, v8, v14, v13
	v_mul_f32_e32 v14, v38, v12
	v_fma_f32 v4, v4, v14, v13
	v_mul_f32_e32 v14, v36, v12
	v_fma_f32 v9, v9, v14, v13
	v_mul_f32_e32 v14, v34, v12
	v_fma_f32 v5, v5, v14, v13
	v_mul_f32_e32 v14, v32, v12
	v_fma_f32 v10, v10, v14, v13
	v_mul_f32_e32 v14, v30, v12
	v_fma_f32 v6, v6, v14, v13
	v_mul_f32_e32 v14, v28, v12
	v_mul_f32_e32 v12, v42, v12
	v_fma_f32 v11, v11, v14, v13
	v_fmac_f32_e32 v13, v7, v12
	v_cvt_pk_bf16_f32 v4, v8, v4
	v_cvt_pk_bf16_f32 v5, v9, v5
	v_cvt_pk_bf16_f32 v6, v10, v6
	v_cvt_pk_bf16_f32 v7, v11, v13
	global_store_dwordx4 v[50:51], v[4:7], off
	s_nop 2
	v_mov_b32_e32 v8, v215
	v_mov_b32_e32 v9, v235
	v_lshlrev_b32_e32 v4, 16, v0
	v_and_b32_e32 v0, 0xffff0000, v0
	v_sub_f32_e32 v4, v4, v41
	v_lshlrev_b32_e32 v5, 16, v1
	v_sub_f32_e32 v0, v0, v39
	v_and_b32_e32 v1, 0xffff0000, v1
	v_sub_f32_e32 v5, v5, v37
	v_lshlrev_b32_e32 v6, 16, v2
	v_sub_f32_e32 v1, v1, v35
	v_and_b32_e32 v2, 0xffff0000, v2
	v_sub_f32_e32 v6, v6, v33
	v_lshlrev_b32_e32 v7, 16, v3
	v_and_b32_e32 v3, 0xffff0000, v3
	v_sub_f32_e32 v2, v2, v31
	v_sub_f32_e32 v7, v7, v29
	v_sub_f32_e32 v3, v3, v43
	v_mul_f32_e32 v10, v40, v8
	v_fma_f32 v4, v4, v10, v9
	v_mul_f32_e32 v10, v38, v8
	v_fma_f32 v0, v0, v10, v9
	v_mul_f32_e32 v10, v36, v8
	v_fma_f32 v5, v5, v10, v9
	v_mul_f32_e32 v10, v34, v8
	v_fma_f32 v1, v1, v10, v9
	v_mul_f32_e32 v10, v32, v8
	v_fma_f32 v6, v6, v10, v9
	v_mul_f32_e32 v10, v30, v8
	v_fma_f32 v2, v2, v10, v9
	v_mul_f32_e32 v10, v28, v8
	v_mul_f32_e32 v8, v42, v8
	v_fma_f32 v7, v7, v10, v9
	v_fmac_f32_e32 v9, v3, v8
	v_cvt_pk_bf16_f32 v0, v4, v0
	v_cvt_pk_bf16_f32 v1, v5, v1
	v_cvt_pk_bf16_f32 v2, v6, v2
	v_cvt_pk_bf16_f32 v3, v7, v9
	global_store_dwordx4 v[48:49], v[0:3], off
	s_branch .LBB0_420
